# v32 + SGU results written in place into the wave's own UZ LDS rows and stored with 8 row-contiguous dwordx4 instead of 16 scattered dwordx2
# speedup vs baseline: 1.0225x; 1.0079x over previous
.LBB0_123:
	s_andn2_b64 vcc, exec, s[8:9]
	s_cbranch_vccnz .LBB0_126
	s_lshl_b32 s2, s23, 4
	v_and_b32_e32 v176, 15, v200
	v_lshrrev_b32_e32 v0, 5, v201
	v_or_b32_e32 v80, s2, v176
	v_or_b32_e32 v98, s2, v0
	v_ashrrev_i32_e32 v81, 31, v80
	v_readlane_b32 s2, v245, 20
	v_lshrrev_b32_e32 v1, 2, v200
	v_lshlrev_b64 v[2:3], 8, v[80:81]
	v_readlane_b32 s3, v245, 21
	v_and_b32_e32 v4, 12, v1
	v_lshlrev_b32_e32 v0, 3, v200
	v_lshl_add_u64 v[2:3], s[2:3], 0, v[2:3]
	v_lshlrev_b32_e32 v154, 1, v4
	v_and_b32_e32 v0, 0xf8, v0
	v_lshl_add_u64 v[2:3], v[2:3], 0, v[154:155]
	s_mov_b64 s[2:3], 0x2640000
	v_readlane_b32 s48, v247, 18
	v_lshl_add_u64 v[82:83], v[2:3], 0, s[2:3]
	v_lshlrev_b32_e32 v2, 2, v0
	v_mov_b32_e32 v3, v155
	v_readlane_b32 s50, v247, 20
	v_readlane_b32 s51, v247, 21
	s_movk_i32 s3, 0x220
	v_readlane_b32 s2, v245, 3
	v_lshl_add_u64 v[84:85], s[50:51], 0, v[2:3]
	v_mul_lo_u32 v3, v80, s3
	v_add3_u32 v81, s2, v3, v154
	v_lshrrev_b32_e32 v3, 2, v201
	v_lshlrev_b32_e32 v5, 3, v201
	v_and_b32_e32 v1, 64, v199
	v_mul_u32_u24_e32 v3, 0x220, v3
	v_and_b32_e32 v5, 24, v5
	v_add_u32_e32 v1, 64, v1
	v_add3_u32 v99, 0, v3, v5
	v_xor_b32_e32 v3, 1, v199
	v_cmp_lt_i32_e32 vcc, v3, v1
	v_lshlrev_b32_e32 v2, 1, v0
	v_readlane_b32 s54, v247, 24
	v_cndmask_b32_e32 v3, v199, v3, vcc
	v_lshlrev_b32_e32 v100, 2, v3
	v_xor_b32_e32 v3, 2, v199
	v_cmp_lt_i32_e32 vcc, v3, v1
	v_readlane_b32 s55, v247, 25
	v_lshlrev_b32_e32 v154, 1, v0
	v_cndmask_b32_e32 v3, v199, v3, vcc
	v_lshlrev_b32_e32 v101, 2, v3
	v_xor_b32_e32 v3, 4, v199
	v_cmp_lt_i32_e32 vcc, v3, v1
	v_lshlrev_b32_e32 v86, 1, v4
	s_mov_b32 s12, 0xa000
	v_cndmask_b32_e32 v3, v199, v3, vcc
	v_lshlrev_b32_e32 v102, 2, v3
	v_xor_b32_e32 v3, 8, v199
	v_cmp_lt_i32_e32 vcc, v3, v1
	v_readlane_b32 s49, v247, 19
	v_readlane_b32 s52, v247, 22
	v_cndmask_b32_e32 v3, v199, v3, vcc
	v_lshlrev_b32_e32 v103, 2, v3
	v_xor_b32_e32 v3, 16, v199
	v_cmp_lt_i32_e32 vcc, v3, v1
	v_readlane_b32 s53, v247, 23
	v_readlane_b32 s56, v247, 26
	v_cndmask_b32_e32 v1, v199, v3, vcc
	v_lshlrev_b32_e32 v104, 2, v1
	v_mul_lo_u32 v1, v98, s3
	v_add3_u32 v105, 0, v2, v1
	v_add3_u32 v106, s2, v2, v1
	v_readlane_b32 s2, v246, 63
	s_mov_b32 s3, s47
	v_readlane_b32 s57, v247, 27
	v_readlane_b32 s58, v247, 28
	v_readlane_b32 s59, v247, 29
	v_readlane_b32 s60, v247, 30
	v_readlane_b32 s61, v247, 31
	v_readlane_b32 s62, v247, 32
	v_readlane_b32 s63, v247, 33
	v_lshrrev_b32_e32 v248, 5, v199
	v_and_b32_e32 v250, 31, v199
	v_mul_u32_u24_e32 v249, 0x220, v248
	v_lshl_add_u32 v249, v250, 4, v249
	v_mul_u32_u24_e32 v248, 0x1080, v248
	v_lshl_add_u32 v248, v250, 4, v248
.LBB0_125:
	s_and_b32 s10, s2, 0xffffff80
	v_add_u32_e32 v2, s10, v98
	v_mov_b64_e32 v[0:1], s[92:93]
	s_and_b32 s11, s3, 3
	v_mad_i64_i32 v[0:1], s[8:9], v2, s33, v[0:1]
	s_lshl_b32 s8, s11, 9
	s_mov_b32 s9, s96
	v_lshl_add_u64 v[0:1], v[0:1], 0, s[8:9]
	v_lshl_add_u64 v[20:21], v[0:1], 0, v[154:155]
	global_load_dwordx4 v[22:25], v[20:21], off offset:2048
	s_mov_b32 s25, s96
	s_mov_b32 s27, s96
	s_lshl_b32 s24, s11, 15
	s_lshl_b32 s26, s11, 10
	v_add_co_u32_e32 v26, vcc, s35, v20
	v_lshl_add_u64 v[88:89], v[82:83], 0, s[24:25]
	v_lshl_add_u64 v[12:13], v[84:85], 0, s[26:27]
	v_addc_co_u32_e32 v27, vcc, 0, v21, vcc
	global_load_dwordx2 v[4:5], v[88:89], off
	global_load_dwordx2 v[6:7], v[88:89], off offset:32
	global_load_dwordx2 v[0:1], v[88:89], off offset:64
	global_load_dwordx2 v[2:3], v[88:89], off offset:96
	global_load_dwordx4 v[8:11], v[12:13], off offset:16
	s_nop 0
	global_load_dwordx4 v[12:15], v[12:13], off
	s_nop 0
	global_load_dwordx4 v[72:75], v[20:21], off
	global_load_dwordx4 v[16:19], v[26:27], off offset:2304
	global_load_dwordx4 v[56:59], v[26:27], off offset:256
	v_add_co_u32_e32 v28, vcc, s12, v20
	s_mov_b32 s13, 0xf000
	s_nop 0
	v_addc_co_u32_e32 v29, vcc, 0, v21, vcc
	v_add_co_u32_e32 v26, vcc, s13, v20
	global_load_dwordx4 v[76:79], v[28:29], off offset:2560
	global_load_dwordx4 v[44:47], v[28:29], off offset:512
	v_addc_co_u32_e32 v27, vcc, 0, v21, vcc
	global_load_dwordx4 v[68:71], v[26:27], off offset:2816
	global_load_dwordx4 v[32:35], v[26:27], off offset:768
	s_mov_b32 s13, 0x14000
	v_add_co_u32_e32 v28, vcc, s13, v20
	s_mov_b32 s13, 0x19000
	s_nop 0
	v_addc_co_u32_e32 v29, vcc, 0, v21, vcc
	v_add_co_u32_e32 v26, vcc, s13, v20
	s_mov_b32 s13, 0x1e000
	s_waitcnt vmcnt(13)
	v_and_b32_e32 v97, 0xffff0000, v22
	v_lshlrev_b32_e32 v94, 16, v23
	v_lshlrev_b32_e32 v96, 16, v22
	v_mul_f32_e32 v36, v97, v97
	v_and_b32_e32 v95, 0xffff0000, v23
	v_add_f32_e32 v27, 0, v96
	v_mov_b32_e32 v30, v94
	v_mov_b32_e32 v31, v97
	v_pk_fma_f32 v[36:37], v[96:97], v[96:97], v[36:37] op_sel_hi:[1,1,0]
	v_lshlrev_b32_e32 v92, 16, v24
	v_mul_f32_e32 v38, v95, v95
	v_add_f32_e32 v27, v27, v97
	v_pk_fma_f32 v[30:31], v[30:31], v[30:31], v[36:37]
	v_lshlrev_b32_e32 v90, 16, v25
	v_and_b32_e32 v91, 0xffff0000, v25
	v_and_b32_e32 v93, 0xffff0000, v24
	v_mov_b32_e32 v24, v92
	v_mov_b32_e32 v25, v95
	v_add_f32_e32 v27, v27, v94
	v_pk_add_f32 v[30:31], v[38:39], v[30:31] op_sel_hi:[0,1]
	v_mul_f32_e32 v40, v93, v93
	v_add_f32_e32 v27, v27, v95
	v_pk_fma_f32 v[24:25], v[24:25], v[24:25], v[30:31]
	v_mov_b32_e32 v22, v90
	v_mov_b32_e32 v23, v93
	v_add_f32_e32 v27, v27, v92
	v_pk_add_f32 v[24:25], v[40:41], v[24:25] op_sel_hi:[0,1]
	v_add_f32_e32 v27, v27, v93
	v_pk_fma_f32 v[22:23], v[22:23], v[22:23], v[24:25]
	v_mul_f32_e32 v42, v91, v91
	v_add_f32_e32 v43, v27, v90
	v_mov_b32_e32 v23, v91
	v_pk_add_f32 v[22:23], v[42:43], v[22:23]
	ds_bpermute_b32 v25, v100, v23
	ds_bpermute_b32 v24, v100, v22
	v_addc_co_u32_e32 v27, vcc, 0, v21, vcc
	v_add_co_u32_e32 v38, vcc, s13, v20
	s_waitcnt lgkmcnt(0)
	v_pk_add_f32 v[22:23], v[22:23], v[24:25]
	ds_bpermute_b32 v37, v101, v23
	ds_bpermute_b32 v36, v101, v22
	v_addc_co_u32_e32 v39, vcc, 0, v21, vcc
	s_mov_b32 s13, 0x23000
	v_add_co_u32_e32 v20, vcc, s13, v20
	s_waitcnt lgkmcnt(0)
	v_pk_add_f32 v[22:23], v[22:23], v[36:37]
	ds_bpermute_b32 v37, v102, v23
	ds_bpermute_b32 v36, v102, v22
	v_addc_co_u32_e32 v21, vcc, 0, v21, vcc
	global_load_dwordx4 v[60:63], v[28:29], off offset:3072
	s_nop 0
	global_load_dwordx4 v[28:31], v[28:29], off offset:1024
	s_nop 0
	global_load_dwordx4 v[48:51], v[26:27], off offset:3328
	s_nop 0
	global_load_dwordx4 v[24:27], v[26:27], off offset:1280
	s_waitcnt lgkmcnt(0)
	v_pk_add_f32 v[22:23], v[22:23], v[36:37]
	ds_bpermute_b32 v41, v103, v23
	ds_bpermute_b32 v40, v103, v22
	global_load_dwordx4 v[64:67], v[38:39], off offset:3584
	s_nop 0
	global_load_dwordx4 v[36:39], v[38:39], off offset:1536
	s_waitcnt vmcnt(11)
	v_lshlrev_b32_e32 v120, 16, v16
	v_lshlrev_b32_e32 v112, 16, v19
	v_and_b32_e32 v113, 0xffff0000, v19
	s_waitcnt lgkmcnt(0)
	v_pk_add_f32 v[22:23], v[22:23], v[40:41]
	ds_bpermute_b32 v109, v104, v23
	ds_bpermute_b32 v108, v104, v22
	global_load_dwordx4 v[52:55], v[20:21], off offset:3840
	global_load_dwordx4 v[40:43], v[20:21], off offset:1792
	v_and_b32_e32 v121, 0xffff0000, v16
	v_add_f32_e32 v16, 0, v120
	v_lshlrev_b32_e32 v118, 16, v17
	s_waitcnt lgkmcnt(0)
	v_pk_add_f32 v[20:21], v[22:23], v[108:109]
	v_add_f32_e32 v107, v16, v121
	v_pk_mul_f32 v[116:117], v[20:21], s[40:41] op_sel_hi:[1,0]
	v_mul_f32_e32 v22, v121, v121
	v_fma_f32 v19, -v117, v117, v116
	v_max_f32_e32 v19, 0, v19
	v_add_f32_e32 v19, 0x358637bd, v19
	v_and_b32_e32 v119, 0xffff0000, v17
	v_mov_b32_e32 v16, v118
	v_mov_b32_e32 v17, v121
	v_pk_fma_f32 v[22:23], v[120:121], v[120:121], v[22:23] op_sel_hi:[1,1,0]
	v_add_f32_e32 v107, v107, v118
	v_lshlrev_b32_e32 v114, 16, v18
	v_mul_f32_e32 v20, 0x4b800000, v19
	v_cmp_gt_f32_e32 vcc, s19, v19
	v_pk_fma_f32 v[16:17], v[16:17], v[16:17], v[22:23]
	v_add_f32_e32 v23, v107, v119
	v_mul_f32_e32 v22, v119, v119
	v_cndmask_b32_e32 v19, v19, v20, vcc
	v_and_b32_e32 v115, 0xffff0000, v18
	v_mov_b32_e32 v20, v114
	v_mov_b32_e32 v21, v119
	v_pk_add_f32 v[16:17], v[22:23], v[16:17] op_sel_hi:[0,1]
	v_add_f32_e32 v22, v23, v114
	v_pk_fma_f32 v[16:17], v[20:21], v[20:21], v[16:17]
	v_add_f32_e32 v21, v22, v115
	v_mul_f32_e32 v20, v115, v115
	v_rsq_f32_e32 v87, v19
	v_mov_b32_e32 v18, v112
	v_mov_b32_e32 v19, v115
	v_pk_add_f32 v[16:17], v[20:21], v[16:17] op_sel_hi:[0,1]
	v_pk_fma_f32 v[16:17], v[18:19], v[18:19], v[16:17]
	v_add_f32_e32 v21, v21, v112
	v_mul_f32_e32 v20, v113, v113
	v_mov_b32_e32 v17, v113
	v_pk_add_f32 v[108:109], v[20:21], v[16:17]
	ds_bpermute_b32 v111, v100, v109
	ds_bpermute_b32 v110, v100, v108
	global_load_dwordx2 v[20:21], v[88:89], off offset:128
	global_load_dwordx2 v[22:23], v[88:89], off offset:160
	global_load_dwordx2 v[16:17], v[88:89], off offset:192
	global_load_dwordx2 v[18:19], v[88:89], off offset:224
	v_mul_f32_e32 v107, 0x45800000, v87
	v_cndmask_b32_e32 v122, v87, v107, vcc
	v_pk_add_f32 v[96:97], v[96:97], v[116:117] op_sel:[0,1] neg_lo:[0,1] neg_hi:[0,1]
	s_waitcnt lgkmcnt(0)
	v_pk_add_f32 v[88:89], v[108:109], v[110:111]
	ds_bpermute_b32 v109, v101, v89
	ds_bpermute_b32 v108, v101, v88
	v_pk_mul_f32 v[96:97], v[96:97], v[122:123] op_sel_hi:[1,0]
	v_pk_add_f32 v[94:95], v[94:95], v[116:117] op_sel:[0,1] neg_lo:[0,1] neg_hi:[0,1]
	v_pk_mul_f32 v[96:97], v[12:13], v[96:97]
	v_pk_mul_f32 v[94:95], v[94:95], v[122:123] op_sel_hi:[1,0]
	s_waitcnt lgkmcnt(0)
	v_pk_add_f32 v[88:89], v[88:89], v[108:109]
	ds_bpermute_b32 v111, v102, v89
	ds_bpermute_b32 v110, v102, v88
	v_cvt_pk_bf16_f32 v108, v96, v97
	v_pk_mul_f32 v[94:95], v[14:15], v[94:95]
	v_pk_add_f32 v[92:93], v[92:93], v[116:117] op_sel:[0,1] neg_lo:[0,1] neg_hi:[0,1]
	v_cvt_pk_bf16_f32 v109, v94, v95
	s_waitcnt lgkmcnt(0)
	v_pk_add_f32 v[88:89], v[88:89], v[110:111]
	ds_bpermute_b32 v97, v103, v89
	ds_bpermute_b32 v96, v103, v88
	v_pk_add_f32 v[90:91], v[90:91], v[116:117] op_sel:[0,1] neg_lo:[0,1] neg_hi:[0,1]
	v_pk_mul_f32 v[92:93], v[92:93], v[122:123] op_sel_hi:[1,0]
	v_pk_mul_f32 v[90:91], v[90:91], v[122:123] op_sel_hi:[1,0]
	s_waitcnt vmcnt(15)
	v_lshlrev_b32_e32 v122, 16, v76
	s_waitcnt lgkmcnt(0)
	v_pk_add_f32 v[88:89], v[88:89], v[96:97]
	ds_bpermute_b32 v95, v104, v89
	ds_bpermute_b32 v94, v104, v88
	v_and_b32_e32 v123, 0xffff0000, v76
	v_lshlrev_b32_e32 v96, 16, v77
	v_add_f32_e32 v76, 0, v122
	v_mul_f32_e32 v124, v123, v123
	s_waitcnt lgkmcnt(0)
	v_pk_add_f32 v[88:89], v[88:89], v[94:95]
	v_and_b32_e32 v97, 0xffff0000, v77
	v_pk_mul_f32 v[88:89], v[88:89], s[40:41] op_sel_hi:[1,0]
	v_add_f32_e32 v107, v76, v123
	v_fma_f32 v87, -v89, v89, v88
	v_max_f32_e32 v87, 0, v87
	v_mov_b32_e32 v76, v96
	v_mov_b32_e32 v77, v123
	v_pk_fma_f32 v[124:125], v[122:123], v[122:123], v[124:125] op_sel_hi:[1,1,0]
	v_pk_mul_f32 v[92:93], v[8:9], v[92:93]
	v_add_f32_e32 v87, 0x358637bd, v87
	v_lshlrev_b32_e32 v94, 16, v78
	v_pk_fma_f32 v[76:77], v[76:77], v[76:77], v[124:125]
	v_mul_f32_e32 v124, v97, v97
	v_cvt_pk_bf16_f32 v110, v92, v93
	v_mul_f32_e32 v92, 0x4b800000, v87
	v_cmp_gt_f32_e32 vcc, s19, v87
	v_and_b32_e32 v95, 0xffff0000, v78
	v_mov_b32_e32 v116, v94
	v_mov_b32_e32 v117, v97
	v_add_f32_e32 v107, v107, v96
	v_pk_add_f32 v[76:77], v[124:125], v[76:77] op_sel_hi:[0,1]
	v_cndmask_b32_e32 v87, v87, v92, vcc
	v_lshlrev_b32_e32 v92, 16, v79
	v_add_f32_e32 v107, v107, v97
	v_pk_fma_f32 v[76:77], v[116:117], v[116:117], v[76:77]
	v_mul_f32_e32 v116, v95, v95
	v_and_b32_e32 v93, 0xffff0000, v79
	v_mov_b32_e32 v78, v92
	v_mov_b32_e32 v79, v95
	v_add_f32_e32 v107, v107, v94
	v_pk_add_f32 v[76:77], v[116:117], v[76:77] op_sel_hi:[0,1]
	v_add_f32_e32 v107, v107, v95
	v_pk_fma_f32 v[76:77], v[78:79], v[78:79], v[76:77]
	v_add_f32_e32 v117, v107, v92
	v_mul_f32_e32 v116, v93, v93
	v_mov_b32_e32 v77, v93
	v_pk_add_f32 v[76:77], v[116:117], v[76:77]
	ds_bpermute_b32 v79, v100, v77
	ds_bpermute_b32 v78, v100, v76
	v_pk_mul_f32 v[90:91], v[10:11], v[90:91]
	v_rsq_f32_e32 v87, v87
	v_cvt_pk_bf16_f32 v111, v90, v91
	ds_write_b128 v105, v[108:111]
	ds_write_b128 v106, v[72:75]
	s_waitcnt lgkmcnt(2)
	v_pk_add_f32 v[72:73], v[76:77], v[78:79]
	ds_bpermute_b32 v75, v101, v73
	ds_bpermute_b32 v74, v101, v72
	v_mul_f32_e32 v90, 0x45800000, v87
	v_cndmask_b32_e32 v76, v87, v90, vcc
	v_pk_add_f32 v[78:79], v[120:121], v[88:89] op_sel:[0,1] neg_lo:[0,1] neg_hi:[0,1]
	s_waitcnt lgkmcnt(0)
	v_pk_add_f32 v[74:75], v[72:73], v[74:75]
	ds_bpermute_b32 v91, v102, v75
	ds_bpermute_b32 v90, v102, v74
	v_pk_mul_f32 v[78:79], v[78:79], v[76:77] op_sel_hi:[1,0]
	s_waitcnt lgkmcnt(0)
	v_pk_add_f32 v[74:75], v[74:75], v[90:91]
	ds_bpermute_b32 v91, v103, v75
	ds_bpermute_b32 v90, v103, v74
	v_pk_mul_f32 v[78:79], v[12:13], v[78:79]
	s_waitcnt lgkmcnt(0)
	v_pk_add_f32 v[90:91], v[74:75], v[90:91]
	v_cvt_pk_bf16_f32 v72, v78, v79
	v_pk_add_f32 v[78:79], v[118:119], v[88:89] op_sel:[0,1] neg_lo:[0,1] neg_hi:[0,1]
	ds_bpermute_b32 v109, v104, v91
	v_pk_mul_f32 v[78:79], v[78:79], v[76:77] op_sel_hi:[1,0]
	ds_bpermute_b32 v108, v104, v90
	v_pk_mul_f32 v[78:79], v[14:15], v[78:79]
	s_nop 0
	v_cvt_pk_bf16_f32 v73, v78, v79
	v_pk_add_f32 v[78:79], v[114:115], v[88:89] op_sel:[0,1] neg_lo:[0,1] neg_hi:[0,1]
	s_nop 0
	v_pk_mul_f32 v[78:79], v[78:79], v[76:77] op_sel_hi:[1,0]
	s_nop 0
	v_pk_mul_f32 v[78:79], v[8:9], v[78:79]
	s_nop 0
	v_cvt_pk_bf16_f32 v74, v78, v79
	v_pk_add_f32 v[78:79], v[112:113], v[88:89] op_sel:[0,1] neg_lo:[0,1] neg_hi:[0,1]
	s_waitcnt vmcnt(13)
	v_lshlrev_b32_e32 v112, 16, v68
	v_pk_mul_f32 v[76:77], v[78:79], v[76:77] op_sel_hi:[1,0]
	s_waitcnt lgkmcnt(0)
	v_pk_add_f32 v[78:79], v[90:91], v[108:109]
	v_and_b32_e32 v113, 0xffff0000, v68
	v_pk_mul_f32 v[78:79], v[78:79], s[40:41] op_sel_hi:[1,0]
	v_lshlrev_b32_e32 v108, 16, v69
	v_fma_f32 v75, -v79, v79, v78
	v_max_f32_e32 v75, 0, v75
	v_add_f32_e32 v75, 0x358637bd, v75
	v_mul_f32_e32 v87, 0x4b800000, v75
	v_cmp_gt_f32_e32 vcc, s19, v75
	v_add_f32_e32 v68, 0, v112
	v_mul_f32_e32 v114, v113, v113
	v_cndmask_b32_e32 v75, v75, v87, vcc
	v_rsq_f32_e32 v87, v75
	v_and_b32_e32 v109, 0xffff0000, v69
	v_add_f32_e32 v75, v68, v113
	v_mov_b32_e32 v68, v108
	v_mov_b32_e32 v69, v113
	v_pk_fma_f32 v[114:115], v[112:113], v[112:113], v[114:115] op_sel_hi:[1,1,0]
	v_lshlrev_b32_e32 v90, 16, v70
	v_pk_fma_f32 v[68:69], v[68:69], v[68:69], v[114:115]
	v_mul_f32_e32 v114, v109, v109
	v_and_b32_e32 v91, 0xffff0000, v70
	v_mov_b32_e32 v110, v90
	v_mov_b32_e32 v111, v109
	v_add_f32_e32 v75, v75, v108
	v_pk_add_f32 v[68:69], v[114:115], v[68:69] op_sel_hi:[0,1]
	v_lshlrev_b32_e32 v88, 16, v71
	v_add_f32_e32 v75, v75, v109
	v_pk_fma_f32 v[68:69], v[110:111], v[110:111], v[68:69]
	v_mul_f32_e32 v110, v91, v91
	v_and_b32_e32 v89, 0xffff0000, v71
	v_mov_b32_e32 v70, v88
	v_mov_b32_e32 v71, v91
	v_add_f32_e32 v75, v75, v90
	v_pk_add_f32 v[68:69], v[110:111], v[68:69] op_sel_hi:[0,1]
	v_add_f32_e32 v75, v75, v91
	v_pk_fma_f32 v[68:69], v[70:71], v[70:71], v[68:69]
	v_add_f32_e32 v111, v75, v88
	v_mul_f32_e32 v110, v89, v89
	v_mov_b32_e32 v69, v89
	v_pk_add_f32 v[68:69], v[110:111], v[68:69]
	ds_bpermute_b32 v71, v100, v69
	ds_bpermute_b32 v70, v100, v68
	v_pk_mul_f32 v[76:77], v[10:11], v[76:77]
	s_nop 0
	v_cvt_pk_bf16_f32 v75, v76, v77
	ds_write_b128 v105, v[72:75] offset:1088
	ds_write_b128 v106, v[56:59] offset:1088
	s_waitcnt lgkmcnt(2)
	v_pk_add_f32 v[56:57], v[68:69], v[70:71]
	ds_bpermute_b32 v59, v101, v57
	ds_bpermute_b32 v58, v101, v56
	v_mul_f32_e32 v72, 0x45800000, v87
	v_cndmask_b32_e32 v68, v87, v72, vcc
	v_pk_add_f32 v[70:71], v[122:123], v[78:79] op_sel:[0,1] neg_lo:[0,1] neg_hi:[0,1]
	s_waitcnt vmcnt(11)
	v_lshlrev_b32_e32 v76, 16, v61
	s_waitcnt lgkmcnt(0)
	v_pk_add_f32 v[58:59], v[56:57], v[58:59]
	ds_bpermute_b32 v73, v102, v59
	ds_bpermute_b32 v72, v102, v58
	v_pk_mul_f32 v[70:71], v[70:71], v[68:69] op_sel_hi:[1,0]
	v_and_b32_e32 v77, 0xffff0000, v61
	v_pk_mul_f32 v[70:71], v[12:13], v[70:71]
	s_waitcnt lgkmcnt(0)
	v_pk_add_f32 v[58:59], v[58:59], v[72:73]
	ds_bpermute_b32 v73, v103, v59
	ds_bpermute_b32 v72, v103, v58
	v_cvt_pk_bf16_f32 v56, v70, v71
	v_pk_add_f32 v[70:71], v[96:97], v[78:79] op_sel:[0,1] neg_lo:[0,1] neg_hi:[0,1]
	s_waitcnt lgkmcnt(0)
	v_pk_add_f32 v[72:73], v[58:59], v[72:73]
	v_pk_mul_f32 v[70:71], v[70:71], v[68:69] op_sel_hi:[1,0]
	ds_bpermute_b32 v75, v104, v73
	v_pk_mul_f32 v[70:71], v[14:15], v[70:71]
	ds_bpermute_b32 v74, v104, v72
	v_cvt_pk_bf16_f32 v57, v70, v71
	v_pk_add_f32 v[70:71], v[94:95], v[78:79] op_sel:[0,1] neg_lo:[0,1] neg_hi:[0,1]
	s_nop 0
	v_pk_mul_f32 v[70:71], v[70:71], v[68:69] op_sel_hi:[1,0]
	s_nop 0
	v_pk_mul_f32 v[70:71], v[8:9], v[70:71]
	s_nop 0
	v_cvt_pk_bf16_f32 v58, v70, v71
	v_pk_add_f32 v[70:71], v[92:93], v[78:79] op_sel:[0,1] neg_lo:[0,1] neg_hi:[0,1]
	v_and_b32_e32 v93, 0xffff0000, v60
	v_pk_mul_f32 v[68:69], v[70:71], v[68:69] op_sel_hi:[1,0]
	s_waitcnt lgkmcnt(0)
	v_pk_add_f32 v[70:71], v[72:73], v[74:75]
	v_lshlrev_b32_e32 v92, 16, v60
	v_pk_mul_f32 v[70:71], v[70:71], s[40:41] op_sel_hi:[1,0]
	v_mul_f32_e32 v94, v93, v93
	v_fma_f32 v59, -v71, v71, v70
	v_max_f32_e32 v59, 0, v59
	v_add_f32_e32 v59, 0x358637bd, v59
	v_mul_f32_e32 v72, 0x4b800000, v59
	v_cmp_gt_f32_e32 vcc, s19, v59
	v_mov_b32_e32 v60, v76
	v_mov_b32_e32 v61, v93
	v_cndmask_b32_e32 v59, v59, v72, vcc
	v_rsq_f32_e32 v87, v59
	v_add_f32_e32 v59, 0, v92
	v_pk_fma_f32 v[94:95], v[92:93], v[92:93], v[94:95] op_sel_hi:[1,1,0]
	v_lshlrev_b32_e32 v74, 16, v62
	v_add_f32_e32 v59, v59, v93
	v_pk_fma_f32 v[60:61], v[60:61], v[60:61], v[94:95]
	v_mul_f32_e32 v94, v77, v77
	v_and_b32_e32 v75, 0xffff0000, v62
	v_mov_b32_e32 v78, v74
	v_mov_b32_e32 v79, v77
	v_add_f32_e32 v59, v59, v76
	v_pk_add_f32 v[60:61], v[94:95], v[60:61] op_sel_hi:[0,1]
	v_lshlrev_b32_e32 v72, 16, v63
	v_add_f32_e32 v59, v59, v77
	v_pk_fma_f32 v[60:61], v[78:79], v[78:79], v[60:61]
	v_mul_f32_e32 v78, v75, v75
	v_and_b32_e32 v73, 0xffff0000, v63
	v_mov_b32_e32 v62, v72
	v_mov_b32_e32 v63, v75
	v_add_f32_e32 v59, v59, v74
	v_pk_add_f32 v[60:61], v[78:79], v[60:61] op_sel_hi:[0,1]
	v_add_f32_e32 v59, v59, v75
	v_pk_fma_f32 v[60:61], v[62:63], v[62:63], v[60:61]
	v_add_f32_e32 v79, v59, v72
	v_mul_f32_e32 v78, v73, v73
	v_mov_b32_e32 v61, v73
	v_pk_add_f32 v[60:61], v[78:79], v[60:61]
	ds_bpermute_b32 v63, v100, v61
	ds_bpermute_b32 v62, v100, v60
	v_pk_mul_f32 v[68:69], v[10:11], v[68:69]
	s_waitcnt vmcnt(9)
	v_and_b32_e32 v79, 0xffff0000, v48
	v_cvt_pk_bf16_f32 v59, v68, v69
	ds_write_b128 v105, v[56:59] offset:2176
	ds_write_b128 v106, v[44:47] offset:2176
	s_waitcnt lgkmcnt(2)
	v_pk_add_f32 v[44:45], v[60:61], v[62:63]
	ds_bpermute_b32 v47, v101, v45
	ds_bpermute_b32 v46, v101, v44
	v_mul_f32_e32 v56, 0x45800000, v87
	v_cndmask_b32_e32 v56, v87, v56, vcc
	v_pk_add_f32 v[58:59], v[112:113], v[70:71] op_sel:[0,1] neg_lo:[0,1] neg_hi:[0,1]
	v_lshlrev_b32_e32 v68, 16, v49
	s_waitcnt lgkmcnt(0)
	v_pk_add_f32 v[46:47], v[44:45], v[46:47]
	ds_bpermute_b32 v61, v102, v47
	ds_bpermute_b32 v60, v102, v46
	v_pk_mul_f32 v[58:59], v[58:59], v[56:57] op_sel_hi:[1,0]
	v_lshlrev_b32_e32 v78, 16, v48
	v_pk_mul_f32 v[58:59], v[12:13], v[58:59]
	v_and_b32_e32 v69, 0xffff0000, v49
	s_waitcnt lgkmcnt(0)
	v_pk_add_f32 v[46:47], v[46:47], v[60:61]
	ds_bpermute_b32 v61, v103, v47
	ds_bpermute_b32 v60, v103, v46
	v_cvt_pk_bf16_f32 v44, v58, v59
	v_pk_add_f32 v[58:59], v[108:109], v[70:71] op_sel:[0,1] neg_lo:[0,1] neg_hi:[0,1]
	v_mov_b32_e32 v48, v68
	v_pk_mul_f32 v[58:59], v[58:59], v[56:57] op_sel_hi:[1,0]
	s_waitcnt lgkmcnt(0)
	v_pk_add_f32 v[60:61], v[46:47], v[60:61]
	v_pk_mul_f32 v[58:59], v[14:15], v[58:59]
	ds_bpermute_b32 v63, v104, v61
	ds_bpermute_b32 v62, v104, v60
	v_cvt_pk_bf16_f32 v45, v58, v59
	v_pk_add_f32 v[58:59], v[90:91], v[70:71] op_sel:[0,1] neg_lo:[0,1] neg_hi:[0,1]
	v_mov_b32_e32 v49, v79
	v_pk_mul_f32 v[58:59], v[58:59], v[56:57] op_sel_hi:[1,0]
	s_nop 0
	v_pk_mul_f32 v[58:59], v[8:9], v[58:59]
	s_nop 0
	v_cvt_pk_bf16_f32 v46, v58, v59
	v_pk_add_f32 v[58:59], v[88:89], v[70:71] op_sel:[0,1] neg_lo:[0,1] neg_hi:[0,1]
	v_mul_f32_e32 v88, v79, v79
	v_pk_mul_f32 v[56:57], v[58:59], v[56:57] op_sel_hi:[1,0]
	s_waitcnt lgkmcnt(0)
	v_pk_add_f32 v[58:59], v[60:61], v[62:63]
	v_pk_fma_f32 v[88:89], v[78:79], v[78:79], v[88:89] op_sel_hi:[1,1,0]
	v_pk_mul_f32 v[58:59], v[58:59], s[40:41] op_sel_hi:[1,0]
	v_lshlrev_b32_e32 v62, 16, v50
	v_fma_f32 v47, -v59, v59, v58
	v_max_f32_e32 v47, 0, v47
	v_add_f32_e32 v47, 0x358637bd, v47
	v_mul_f32_e32 v60, 0x4b800000, v47
	v_cmp_gt_f32_e32 vcc, s19, v47
	v_pk_fma_f32 v[48:49], v[48:49], v[48:49], v[88:89]
	v_mul_f32_e32 v88, v69, v69
	v_cndmask_b32_e32 v47, v47, v60, vcc
	v_rsq_f32_e32 v87, v47
	v_add_f32_e32 v47, 0, v78
	v_add_f32_e32 v47, v47, v79
	v_and_b32_e32 v63, 0xffff0000, v50
	v_mov_b32_e32 v70, v62
	v_mov_b32_e32 v71, v69
	v_add_f32_e32 v47, v47, v68
	v_pk_add_f32 v[48:49], v[88:89], v[48:49] op_sel_hi:[0,1]
	v_lshlrev_b32_e32 v60, 16, v51
	v_add_f32_e32 v47, v47, v69
	v_pk_fma_f32 v[48:49], v[70:71], v[70:71], v[48:49]
	v_mul_f32_e32 v70, v63, v63
	v_and_b32_e32 v61, 0xffff0000, v51
	v_mov_b32_e32 v50, v60
	v_mov_b32_e32 v51, v63
	v_add_f32_e32 v47, v47, v62
	v_pk_add_f32 v[48:49], v[70:71], v[48:49] op_sel_hi:[0,1]
	v_add_f32_e32 v47, v47, v63
	v_pk_fma_f32 v[48:49], v[50:51], v[50:51], v[48:49]
	v_add_f32_e32 v71, v47, v60
	v_mul_f32_e32 v70, v61, v61
	v_mov_b32_e32 v49, v61
	v_pk_add_f32 v[48:49], v[70:71], v[48:49]
	ds_bpermute_b32 v51, v100, v49
	ds_bpermute_b32 v50, v100, v48
	v_pk_mul_f32 v[56:57], v[10:11], v[56:57]
	s_waitcnt vmcnt(7)
	v_and_b32_e32 v71, 0xffff0000, v64
	v_cvt_pk_bf16_f32 v47, v56, v57
	ds_write_b128 v105, v[44:47] offset:3264
	ds_write_b128 v106, v[32:35] offset:3264
	s_waitcnt lgkmcnt(2)
	v_pk_add_f32 v[32:33], v[48:49], v[50:51]
	ds_bpermute_b32 v35, v101, v33
	ds_bpermute_b32 v34, v101, v32
	v_mul_f32_e32 v44, 0x45800000, v87
	v_cndmask_b32_e32 v44, v87, v44, vcc
	v_pk_add_f32 v[46:47], v[92:93], v[58:59] op_sel:[0,1] neg_lo:[0,1] neg_hi:[0,1]
	v_lshlrev_b32_e32 v70, 16, v64
	s_waitcnt lgkmcnt(0)
	v_pk_add_f32 v[34:35], v[32:33], v[34:35]
	ds_bpermute_b32 v49, v102, v35
	ds_bpermute_b32 v48, v102, v34
	v_pk_mul_f32 v[46:47], v[46:47], v[44:45] op_sel_hi:[1,0]
	s_waitcnt lgkmcnt(0)
	v_pk_add_f32 v[34:35], v[34:35], v[48:49]
	ds_bpermute_b32 v49, v103, v35
	ds_bpermute_b32 v48, v103, v34
	v_pk_mul_f32 v[46:47], v[12:13], v[46:47]
	s_waitcnt lgkmcnt(0)
	v_pk_add_f32 v[48:49], v[34:35], v[48:49]
	v_cvt_pk_bf16_f32 v32, v46, v47
	v_pk_add_f32 v[46:47], v[76:77], v[58:59] op_sel:[0,1] neg_lo:[0,1] neg_hi:[0,1]
	ds_bpermute_b32 v51, v104, v49
	v_pk_mul_f32 v[46:47], v[46:47], v[44:45] op_sel_hi:[1,0]
	ds_bpermute_b32 v50, v104, v48
	v_pk_mul_f32 v[46:47], v[14:15], v[46:47]
	s_nop 0
	v_cvt_pk_bf16_f32 v33, v46, v47
	v_pk_add_f32 v[46:47], v[74:75], v[58:59] op_sel:[0,1] neg_lo:[0,1] neg_hi:[0,1]
	s_nop 0
	v_pk_mul_f32 v[46:47], v[46:47], v[44:45] op_sel_hi:[1,0]
	s_nop 0
	v_pk_mul_f32 v[46:47], v[8:9], v[46:47]
	s_nop 0
	v_cvt_pk_bf16_f32 v34, v46, v47
	v_pk_add_f32 v[46:47], v[72:73], v[58:59] op_sel:[0,1] neg_lo:[0,1] neg_hi:[0,1]
	v_lshlrev_b32_e32 v58, 16, v65
	v_pk_mul_f32 v[44:45], v[46:47], v[44:45] op_sel_hi:[1,0]
	s_waitcnt lgkmcnt(0)
	v_pk_add_f32 v[46:47], v[48:49], v[50:51]
	v_mul_f32_e32 v72, v71, v71
	v_pk_mul_f32 v[46:47], v[46:47], s[40:41] op_sel_hi:[1,0]
	v_and_b32_e32 v59, 0xffff0000, v65
	v_fma_f32 v35, -v47, v47, v46
	v_max_f32_e32 v35, 0, v35
	v_add_f32_e32 v35, 0x358637bd, v35
	v_mul_f32_e32 v48, 0x4b800000, v35
	v_cmp_gt_f32_e32 vcc, s19, v35
	v_mov_b32_e32 v64, v58
	v_mov_b32_e32 v65, v71
	v_cndmask_b32_e32 v35, v35, v48, vcc
	v_rsq_f32_e32 v74, v35
	v_add_f32_e32 v35, 0, v70
	v_pk_fma_f32 v[72:73], v[70:71], v[70:71], v[72:73] op_sel_hi:[1,1,0]
	v_lshlrev_b32_e32 v50, 16, v66
	v_add_f32_e32 v35, v35, v71
	v_pk_fma_f32 v[64:65], v[64:65], v[64:65], v[72:73]
	v_mul_f32_e32 v72, v59, v59
	v_lshlrev_b32_e32 v48, 16, v67
	v_and_b32_e32 v49, 0xffff0000, v67
	v_and_b32_e32 v51, 0xffff0000, v66
	v_mov_b32_e32 v66, v50
	v_mov_b32_e32 v67, v59
	v_add_f32_e32 v35, v35, v58
	v_pk_add_f32 v[64:65], v[72:73], v[64:65] op_sel_hi:[0,1]
	v_add_f32_e32 v35, v35, v59
	v_pk_fma_f32 v[64:65], v[66:67], v[66:67], v[64:65]
	v_mul_f32_e32 v66, v51, v51
	v_mov_b32_e32 v56, v48
	v_mov_b32_e32 v57, v51
	v_add_f32_e32 v35, v35, v50
	v_pk_add_f32 v[64:65], v[66:67], v[64:65] op_sel_hi:[0,1]
	v_add_f32_e32 v35, v35, v51
	v_pk_fma_f32 v[56:57], v[56:57], v[56:57], v[64:65]
	v_add_f32_e32 v67, v35, v48
	v_mul_f32_e32 v66, v49, v49
	v_mov_b32_e32 v57, v49
	v_pk_add_f32 v[56:57], v[66:67], v[56:57]
	ds_bpermute_b32 v65, v100, v57
	ds_bpermute_b32 v64, v100, v56
	v_pk_mul_f32 v[44:45], v[10:11], v[44:45]
	s_nop 0
	v_cvt_pk_bf16_f32 v35, v44, v45
	ds_write_b128 v105, v[32:35] offset:4352
	ds_write_b128 v106, v[28:31] offset:4352
	s_waitcnt lgkmcnt(2)
	v_pk_add_f32 v[28:29], v[56:57], v[64:65]
	ds_bpermute_b32 v31, v101, v29
	ds_bpermute_b32 v30, v101, v28
	v_mul_f32_e32 v32, 0x45800000, v74
	v_cndmask_b32_e32 v32, v74, v32, vcc
	v_pk_add_f32 v[34:35], v[78:79], v[46:47] op_sel:[0,1] neg_lo:[0,1] neg_hi:[0,1]
	s_waitcnt lgkmcnt(0)
	v_pk_add_f32 v[30:31], v[28:29], v[30:31]
	ds_bpermute_b32 v45, v102, v31
	ds_bpermute_b32 v44, v102, v30
	v_pk_mul_f32 v[34:35], v[34:35], v[32:33] op_sel_hi:[1,0]
	s_waitcnt lgkmcnt(0)
	v_pk_add_f32 v[30:31], v[30:31], v[44:45]
	ds_bpermute_b32 v45, v103, v31
	ds_bpermute_b32 v44, v103, v30
	v_pk_mul_f32 v[34:35], v[12:13], v[34:35]
	s_waitcnt lgkmcnt(0)
	v_pk_add_f32 v[44:45], v[30:31], v[44:45]
	v_cvt_pk_bf16_f32 v28, v34, v35
	v_pk_add_f32 v[34:35], v[68:69], v[46:47] op_sel:[0,1] neg_lo:[0,1] neg_hi:[0,1]
	ds_bpermute_b32 v57, v104, v45
	v_pk_mul_f32 v[34:35], v[34:35], v[32:33] op_sel_hi:[1,0]
	ds_bpermute_b32 v56, v104, v44
	v_pk_mul_f32 v[34:35], v[14:15], v[34:35]
	s_nop 0
	v_cvt_pk_bf16_f32 v29, v34, v35
	v_pk_add_f32 v[34:35], v[62:63], v[46:47] op_sel:[0,1] neg_lo:[0,1] neg_hi:[0,1]
	s_waitcnt vmcnt(5)
	v_and_b32_e32 v63, 0xffff0000, v52
	v_pk_mul_f32 v[34:35], v[34:35], v[32:33] op_sel_hi:[1,0]
	v_lshlrev_b32_e32 v62, 16, v52
	v_pk_mul_f32 v[34:35], v[8:9], v[34:35]
	v_mul_f32_e32 v64, v63, v63
	v_cvt_pk_bf16_f32 v30, v34, v35
	v_pk_add_f32 v[34:35], v[60:61], v[46:47] op_sel:[0,1] neg_lo:[0,1] neg_hi:[0,1]
	v_pk_fma_f32 v[64:65], v[62:63], v[62:63], v[64:65] op_sel_hi:[1,1,0]
	v_pk_mul_f32 v[32:33], v[34:35], v[32:33] op_sel_hi:[1,0]
	s_waitcnt lgkmcnt(0)
	v_pk_add_f32 v[34:35], v[44:45], v[56:57]
	v_lshlrev_b32_e32 v56, 16, v53
	v_pk_mul_f32 v[34:35], v[34:35], s[40:41] op_sel_hi:[1,0]
	v_and_b32_e32 v57, 0xffff0000, v53
	v_fma_f32 v31, -v35, v35, v34
	v_max_f32_e32 v31, 0, v31
	v_add_f32_e32 v31, 0x358637bd, v31
	v_mul_f32_e32 v44, 0x4b800000, v31
	v_cmp_gt_f32_e32 vcc, s19, v31
	v_mov_b32_e32 v52, v56
	v_mov_b32_e32 v53, v63
	v_cndmask_b32_e32 v31, v31, v44, vcc
	v_rsq_f32_e32 v66, v31
	v_add_f32_e32 v31, 0, v62
	v_lshlrev_b32_e32 v46, 16, v54
	v_add_f32_e32 v31, v31, v63
	v_pk_fma_f32 v[52:53], v[52:53], v[52:53], v[64:65]
	v_mul_f32_e32 v64, v57, v57
	v_and_b32_e32 v47, 0xffff0000, v54
	v_mov_b32_e32 v60, v46
	v_mov_b32_e32 v61, v57
	v_add_f32_e32 v31, v31, v56
	v_pk_add_f32 v[52:53], v[64:65], v[52:53] op_sel_hi:[0,1]
	v_lshlrev_b32_e32 v44, 16, v55
	v_add_f32_e32 v31, v31, v57
	v_pk_fma_f32 v[52:53], v[60:61], v[60:61], v[52:53]
	v_mul_f32_e32 v60, v47, v47
	v_and_b32_e32 v45, 0xffff0000, v55
	v_mov_b32_e32 v54, v44
	v_mov_b32_e32 v55, v47
	v_add_f32_e32 v31, v31, v46
	v_pk_add_f32 v[52:53], v[60:61], v[52:53] op_sel_hi:[0,1]
	v_add_f32_e32 v31, v31, v47
	v_pk_fma_f32 v[52:53], v[54:55], v[54:55], v[52:53]
	v_add_f32_e32 v61, v31, v44
	v_mul_f32_e32 v60, v45, v45
	v_mov_b32_e32 v53, v45
	v_pk_add_f32 v[52:53], v[60:61], v[52:53]
	ds_bpermute_b32 v55, v100, v53
	ds_bpermute_b32 v54, v100, v52
	v_pk_mul_f32 v[32:33], v[10:11], v[32:33]
	s_nop 0
	v_cvt_pk_bf16_f32 v31, v32, v33
	ds_write_b128 v105, v[28:31] offset:5440
	ds_write_b128 v106, v[24:27] offset:5440
	s_waitcnt lgkmcnt(2)
	v_pk_add_f32 v[24:25], v[52:53], v[54:55]
	ds_bpermute_b32 v27, v101, v25
	ds_bpermute_b32 v26, v101, v24
	v_mul_f32_e32 v28, 0x45800000, v66
	v_cndmask_b32_e32 v28, v66, v28, vcc
	v_pk_add_f32 v[30:31], v[70:71], v[34:35] op_sel:[0,1] neg_lo:[0,1] neg_hi:[0,1]
	s_waitcnt lgkmcnt(0)
	v_pk_add_f32 v[26:27], v[24:25], v[26:27]
	ds_bpermute_b32 v33, v102, v27
	ds_bpermute_b32 v32, v102, v26
	v_pk_mul_f32 v[30:31], v[30:31], v[28:29] op_sel_hi:[1,0]
	s_waitcnt lgkmcnt(0)
	v_pk_add_f32 v[26:27], v[26:27], v[32:33]
	ds_bpermute_b32 v33, v103, v27
	ds_bpermute_b32 v32, v103, v26
	v_pk_mul_f32 v[30:31], v[12:13], v[30:31]
	s_waitcnt lgkmcnt(0)
	v_pk_add_f32 v[32:33], v[26:27], v[32:33]
	v_cvt_pk_bf16_f32 v24, v30, v31
	v_pk_add_f32 v[30:31], v[58:59], v[34:35] op_sel:[0,1] neg_lo:[0,1] neg_hi:[0,1]
	s_nop 0
	v_pk_mul_f32 v[30:31], v[30:31], v[28:29] op_sel_hi:[1,0]
	s_nop 0
	v_pk_mul_f32 v[30:31], v[14:15], v[30:31]
	s_nop 0
	v_cvt_pk_bf16_f32 v25, v30, v31
	v_pk_add_f32 v[30:31], v[50:51], v[34:35] op_sel:[0,1] neg_lo:[0,1] neg_hi:[0,1]
	ds_bpermute_b32 v51, v104, v33
	ds_bpermute_b32 v50, v104, v32
	v_pk_mul_f32 v[30:31], v[30:31], v[28:29] op_sel_hi:[1,0]
	s_nop 0
	v_pk_mul_f32 v[30:31], v[8:9], v[30:31]
	s_nop 0
	v_cvt_pk_bf16_f32 v26, v30, v31
	v_pk_add_f32 v[30:31], v[48:49], v[34:35] op_sel:[0,1] neg_lo:[0,1] neg_hi:[0,1]
	s_nop 0
	v_pk_mul_f32 v[28:29], v[30:31], v[28:29] op_sel_hi:[1,0]
	s_waitcnt lgkmcnt(0)
	v_pk_add_f32 v[30:31], v[32:33], v[50:51]
	v_pk_mul_f32 v[28:29], v[10:11], v[28:29]
	v_pk_mul_f32 v[30:31], v[30:31], s[40:41] op_sel_hi:[1,0]
	s_nop 0
	v_fma_f32 v27, -v31, v31, v30
	v_max_f32_e32 v27, 0, v27
	v_add_f32_e32 v27, 0x358637bd, v27
	v_mul_f32_e32 v32, 0x4b800000, v27
	v_cmp_gt_f32_e32 vcc, s19, v27
	s_nop 1
	v_cndmask_b32_e32 v27, v27, v32, vcc
	v_rsq_f32_e32 v32, v27
	v_cvt_pk_bf16_f32 v27, v28, v29
	ds_write_b128 v105, v[24:27] offset:6528
	ds_write_b128 v106, v[36:39] offset:6528
	v_pk_add_f32 v[26:27], v[62:63], v[30:31] op_sel:[0,1] neg_lo:[0,1] neg_hi:[0,1]
	v_mul_f32_e32 v24, 0x45800000, v32
	v_cndmask_b32_e32 v24, v32, v24, vcc
	v_pk_mul_f32 v[26:27], v[26:27], v[24:25] op_sel_hi:[1,0]
	s_nop 0
	v_pk_mul_f32 v[12:13], v[12:13], v[26:27]
	v_pk_add_f32 v[26:27], v[56:57], v[30:31] op_sel:[0,1] neg_lo:[0,1] neg_hi:[0,1]
	v_cvt_pk_bf16_f32 v12, v12, v13
	v_pk_mul_f32 v[26:27], v[26:27], v[24:25] op_sel_hi:[1,0]
	s_nop 0
	v_pk_mul_f32 v[14:15], v[14:15], v[26:27]
	s_nop 0
	v_cvt_pk_bf16_f32 v13, v14, v15
	v_pk_add_f32 v[14:15], v[46:47], v[30:31] op_sel:[0,1] neg_lo:[0,1] neg_hi:[0,1]
	s_nop 0
	v_pk_mul_f32 v[14:15], v[14:15], v[24:25] op_sel_hi:[1,0]
	s_nop 0
	v_pk_mul_f32 v[8:9], v[8:9], v[14:15]
	s_nop 0
	v_cvt_pk_bf16_f32 v14, v8, v9
	v_pk_add_f32 v[8:9], v[44:45], v[30:31] op_sel:[0,1] neg_lo:[0,1] neg_hi:[0,1]
	s_nop 0
	v_pk_mul_f32 v[8:9], v[8:9], v[24:25] op_sel_hi:[1,0]
	s_nop 0
	v_pk_mul_f32 v[8:9], v[10:11], v[8:9]
	s_nop 0
	v_cvt_pk_bf16_f32 v15, v8, v9
	v_lshl_add_u32 v8, s11, 7, v80
	v_ashrrev_i32_e32 v9, 31, v8
	v_lshl_add_u64 v[8:9], v[8:9], 2, s[54:55]
	ds_write_b128 v105, v[12:15] offset:7616
	s_waitcnt vmcnt(4)
	ds_write_b128 v106, v[40:43] offset:7616
	s_waitcnt lgkmcnt(0)
	s_barrier
	global_load_dword v28, v[8:9], off
	ds_read_b64_tr_b16 v[8:9], v99
	ds_read_b64_tr_b16 v[12:13], v99 offset:32
	ds_read_b64_tr_b16 v[24:25], v99 offset:64
	ds_read_b64_tr_b16 v[30:31], v99 offset:96
	ds_read_b64_tr_b16 v[10:11], v99 offset:8704
	ds_read_b64_tr_b16 v[14:15], v99 offset:8736
	ds_read_b64_tr_b16 v[26:27], v99 offset:8768
	ds_read_b64_tr_b16 v[32:33], v99 offset:8800
	ds_read_b64_tr_b16 v[34:35], v99 offset:128
	ds_read_b64_tr_b16 v[38:39], v99 offset:160
	ds_read_b64_tr_b16 v[42:43], v99 offset:192
	ds_read_b64_tr_b16 v[46:47], v99 offset:224
	ds_read_b64_tr_b16 v[36:37], v99 offset:8832
	ds_read_b64_tr_b16 v[40:41], v99 offset:8864
	ds_read_b64_tr_b16 v[44:45], v99 offset:8896
	ds_read_b64_tr_b16 v[48:49], v99 offset:8928
	ds_read_b64_tr_b16 v[50:51], v99 offset:256
	ds_read_b64_tr_b16 v[54:55], v99 offset:288
	ds_read_b64_tr_b16 v[58:59], v99 offset:320
	ds_read_b64_tr_b16 v[62:63], v99 offset:352
	ds_read_b64_tr_b16 v[52:53], v99 offset:8960
	ds_read_b64_tr_b16 v[56:57], v99 offset:8992
	ds_read_b64_tr_b16 v[60:61], v99 offset:9024
	ds_read_b64_tr_b16 v[64:65], v99 offset:9056
	ds_read_b64_tr_b16 v[66:67], v99 offset:384
	ds_read_b64_tr_b16 v[70:71], v99 offset:416
	ds_read_b64_tr_b16 v[74:75], v99 offset:448
	ds_read_b64_tr_b16 v[88:89], v99 offset:480
	ds_read_b64_tr_b16 v[68:69], v99 offset:9088
	ds_read_b64_tr_b16 v[72:73], v99 offset:9120
	ds_read_b64_tr_b16 v[76:77], v99 offset:9152
	ds_read_b64_tr_b16 v[90:91], v99 offset:9184
	ds_read_b64_tr_b16 v[92:93], v99 offset:17408
	ds_read_b64_tr_b16 v[108:109], v99 offset:17440
	ds_read_b64_tr_b16 v[112:113], v99 offset:17472
	ds_read_b64_tr_b16 v[116:117], v99 offset:17504
	ds_read_b64_tr_b16 v[94:95], v99 offset:26112
	ds_read_b64_tr_b16 v[110:111], v99 offset:26144
	ds_read_b64_tr_b16 v[114:115], v99 offset:26176
	ds_read_b64_tr_b16 v[118:119], v99 offset:26208
	ds_read_b64_tr_b16 v[120:121], v99 offset:17536
	ds_read_b64_tr_b16 v[124:125], v99 offset:17568
	ds_read_b64_tr_b16 v[128:129], v99 offset:17600
	ds_read_b64_tr_b16 v[132:133], v99 offset:17632
	ds_read_b64_tr_b16 v[122:123], v99 offset:26240
	ds_read_b64_tr_b16 v[126:127], v99 offset:26272
	ds_read_b64_tr_b16 v[130:131], v99 offset:26304
	ds_read_b64_tr_b16 v[134:135], v99 offset:26336
	ds_read_b64_tr_b16 v[136:137], v99 offset:17664
	ds_read_b64_tr_b16 v[140:141], v99 offset:17696
	ds_read_b64_tr_b16 v[144:145], v99 offset:17728
	ds_read_b64_tr_b16 v[148:149], v99 offset:17760
	ds_read_b64_tr_b16 v[138:139], v99 offset:26368
	ds_read_b64_tr_b16 v[142:143], v99 offset:26400
	ds_read_b64_tr_b16 v[146:147], v99 offset:26432
	ds_read_b64_tr_b16 v[150:151], v99 offset:26464
	ds_read_b64_tr_b16 v[156:157], v99 offset:17792
	ds_read_b64_tr_b16 v[160:161], v99 offset:17824
	ds_read_b64_tr_b16 v[164:165], v99 offset:17856
	ds_read_b64_tr_b16 v[168:169], v99 offset:17888
	ds_read_b64_tr_b16 v[158:159], v99 offset:26496
	ds_read_b64_tr_b16 v[162:163], v99 offset:26528
	ds_read_b64_tr_b16 v[166:167], v99 offset:26560
	ds_read_b64_tr_b16 v[170:171], v99 offset:26592
	s_waitcnt lgkmcnt(14)
	v_mfma_f32_16x16x32_bf16 v[8:11], v[8:11], v[4:7], 0
	v_mfma_f32_16x16x32_bf16 v[12:15], v[12:15], v[4:7], 0
	v_mfma_f32_16x16x32_bf16 v[24:27], v[24:27], v[4:7], 0
	v_mfma_f32_16x16x32_bf16 v[30:33], v[30:33], v[4:7], 0
	v_mfma_f32_16x16x32_bf16 v[34:37], v[34:37], v[4:7], 0
	v_mfma_f32_16x16x32_bf16 v[38:41], v[38:41], v[4:7], 0
	v_mfma_f32_16x16x32_bf16 v[42:45], v[42:45], v[4:7], 0
	v_mfma_f32_16x16x32_bf16 v[46:49], v[46:49], v[4:7], 0
	v_mfma_f32_16x16x32_bf16 v[50:53], v[50:53], v[4:7], 0
	v_mfma_f32_16x16x32_bf16 v[54:57], v[54:57], v[4:7], 0
	v_mfma_f32_16x16x32_bf16 v[58:61], v[58:61], v[4:7], 0
	v_mfma_f32_16x16x32_bf16 v[62:65], v[62:65], v[4:7], 0
	v_mfma_f32_16x16x32_bf16 v[66:69], v[66:69], v[4:7], 0
	v_mfma_f32_16x16x32_bf16 v[70:73], v[70:73], v[4:7], 0
	v_mfma_f32_16x16x32_bf16 v[74:77], v[74:77], v[4:7], 0
	v_mfma_f32_16x16x32_bf16 v[4:7], v[88:91], v[4:7], 0
	ds_read_b64_tr_b16 v[88:89], v99 offset:34816
	ds_read_b64_tr_b16 v[172:173], v99 offset:34848
	ds_read_b64_tr_b16 v[178:179], v99 offset:34880
	ds_read_b64_tr_b16 v[182:183], v99 offset:34912
	ds_read_b64_tr_b16 v[90:91], v99 offset:43520
	ds_read_b64_tr_b16 v[174:175], v99 offset:43552
	ds_read_b64_tr_b16 v[180:181], v99 offset:43584
	ds_read_b64_tr_b16 v[184:185], v99 offset:43616
	ds_read_b64_tr_b16 v[188:189], v99 offset:34944
	ds_read_b64_tr_b16 v[192:193], v99 offset:34976
	ds_read_b64_tr_b16 v[202:203], v99 offset:35008
	ds_read_b64_tr_b16 v[206:207], v99 offset:35040
	ds_read_b64_tr_b16 v[190:191], v99 offset:43648
	ds_read_b64_tr_b16 v[194:195], v99 offset:43680
	ds_read_b64_tr_b16 v[204:205], v99 offset:43712
	ds_read_b64_tr_b16 v[208:209], v99 offset:43744
	ds_read_b64_tr_b16 v[210:211], v99 offset:35072
	ds_read_b64_tr_b16 v[214:215], v99 offset:35104
	ds_read_b64_tr_b16 v[218:219], v99 offset:35136
	ds_read_b64_tr_b16 v[222:223], v99 offset:35168
	ds_read_b64_tr_b16 v[212:213], v99 offset:43776
	ds_read_b64_tr_b16 v[216:217], v99 offset:43808
	ds_read_b64_tr_b16 v[220:221], v99 offset:43840
	ds_read_b64_tr_b16 v[224:225], v99 offset:43872
	ds_read_b64_tr_b16 v[226:227], v99 offset:35200
	ds_read_b64_tr_b16 v[230:231], v99 offset:35232
	ds_read_b64_tr_b16 v[234:235], v99 offset:35264
	ds_read_b64_tr_b16 v[238:239], v99 offset:35296
	ds_read_b64_tr_b16 v[228:229], v99 offset:43904
	ds_read_b64_tr_b16 v[232:233], v99 offset:43936
	ds_read_b64_tr_b16 v[236:237], v99 offset:43968
	ds_read_b64_tr_b16 v[240:241], v99 offset:44000
	v_mfma_f32_16x16x32_bf16 v[8:11], v[92:95], v[0:3], v[8:11]
	v_mfma_f32_16x16x32_bf16 v[12:15], v[108:111], v[0:3], v[12:15]
	v_mfma_f32_16x16x32_bf16 v[24:27], v[112:115], v[0:3], v[24:27]
	v_mfma_f32_16x16x32_bf16 v[30:33], v[116:119], v[0:3], v[30:33]
	v_mfma_f32_16x16x32_bf16 v[34:37], v[120:123], v[0:3], v[34:37]
	v_mfma_f32_16x16x32_bf16 v[38:41], v[124:127], v[0:3], v[38:41]
	v_mfma_f32_16x16x32_bf16 v[42:45], v[128:131], v[0:3], v[42:45]
	v_mfma_f32_16x16x32_bf16 v[46:49], v[132:135], v[0:3], v[46:49]
	s_waitcnt lgkmcnt(14)
	v_mfma_f32_16x16x32_bf16 v[50:53], v[136:139], v[0:3], v[50:53]
	v_mfma_f32_16x16x32_bf16 v[54:57], v[140:143], v[0:3], v[54:57]
	v_mfma_f32_16x16x32_bf16 v[58:61], v[144:147], v[0:3], v[58:61]
	v_mfma_f32_16x16x32_bf16 v[62:65], v[148:151], v[0:3], v[62:65]
	v_mfma_f32_16x16x32_bf16 v[66:69], v[156:159], v[0:3], v[66:69]
	v_mfma_f32_16x16x32_bf16 v[70:73], v[160:163], v[0:3], v[70:73]
	v_mfma_f32_16x16x32_bf16 v[74:77], v[164:167], v[0:3], v[74:77]
	v_mfma_f32_16x16x32_bf16 v[0:3], v[168:171], v[0:3], v[4:7]
	s_nop 2
	ds_read_b64_tr_b16 v[4:5], v99 offset:52224
	ds_read_b64_tr_b16 v[92:93], v99 offset:52256
	ds_read_b64_tr_b16 v[108:109], v99 offset:52288
	ds_read_b64_tr_b16 v[112:113], v99 offset:52320
	ds_read_b64_tr_b16 v[6:7], v99 offset:60928
	ds_read_b64_tr_b16 v[94:95], v99 offset:60960
	ds_read_b64_tr_b16 v[110:111], v99 offset:60992
	ds_read_b64_tr_b16 v[114:115], v99 offset:61024
	ds_read_b64_tr_b16 v[116:117], v99 offset:52352
	ds_read_b64_tr_b16 v[120:121], v99 offset:52384
	ds_read_b64_tr_b16 v[124:125], v99 offset:52416
	ds_read_b64_tr_b16 v[128:129], v99 offset:52448
	ds_read_b64_tr_b16 v[118:119], v99 offset:61056
	ds_read_b64_tr_b16 v[122:123], v99 offset:61088
	ds_read_b64_tr_b16 v[126:127], v99 offset:61120
	ds_read_b64_tr_b16 v[130:131], v99 offset:61152
	ds_read_b64_tr_b16 v[132:133], v99 offset:52480
	ds_read_b64_tr_b16 v[136:137], v99 offset:52512
	ds_read_b64_tr_b16 v[140:141], v99 offset:52544
	ds_read_b64_tr_b16 v[144:145], v99 offset:52576
	ds_read_b64_tr_b16 v[134:135], v99 offset:61184
	ds_read_b64_tr_b16 v[138:139], v99 offset:61216
	ds_read_b64_tr_b16 v[142:143], v99 offset:61248
	ds_read_b64_tr_b16 v[146:147], v99 offset:61280
	ds_read_b64_tr_b16 v[148:149], v99 offset:52608
	ds_read_b64_tr_b16 v[156:157], v99 offset:52640
	ds_read_b64_tr_b16 v[160:161], v99 offset:52672
	ds_read_b64_tr_b16 v[164:165], v99 offset:52704
	ds_read_b64_tr_b16 v[150:151], v99 offset:61312
	ds_read_b64_tr_b16 v[158:159], v99 offset:61344
	ds_read_b64_tr_b16 v[162:163], v99 offset:61376
	ds_read_b64_tr_b16 v[166:167], v99 offset:61408
	s_waitcnt vmcnt(3)
	v_mfma_f32_16x16x32_bf16 v[8:11], v[88:91], v[20:23], v[8:11]
	v_mfma_f32_16x16x32_bf16 v[12:15], v[172:175], v[20:23], v[12:15]
	v_mfma_f32_16x16x32_bf16 v[24:27], v[178:181], v[20:23], v[24:27]
	v_mfma_f32_16x16x32_bf16 v[30:33], v[182:185], v[20:23], v[30:33]
	v_mfma_f32_16x16x32_bf16 v[34:37], v[188:191], v[20:23], v[34:37]
	v_mfma_f32_16x16x32_bf16 v[38:41], v[192:195], v[20:23], v[38:41]
	v_mfma_f32_16x16x32_bf16 v[42:45], v[202:205], v[20:23], v[42:45]
	v_mfma_f32_16x16x32_bf16 v[46:49], v[206:209], v[20:23], v[46:49]
	s_waitcnt lgkmcnt(14)
	v_mfma_f32_16x16x32_bf16 v[50:53], v[210:213], v[20:23], v[50:53]
	v_mfma_f32_16x16x32_bf16 v[54:57], v[214:217], v[20:23], v[54:57]
	v_mfma_f32_16x16x32_bf16 v[58:61], v[218:221], v[20:23], v[58:61]
	v_mfma_f32_16x16x32_bf16 v[62:65], v[222:225], v[20:23], v[62:65]
	v_mfma_f32_16x16x32_bf16 v[66:69], v[226:229], v[20:23], v[66:69]
	v_mfma_f32_16x16x32_bf16 v[70:73], v[230:233], v[20:23], v[70:73]
	v_mfma_f32_16x16x32_bf16 v[74:77], v[234:237], v[20:23], v[74:77]
	v_mfma_f32_16x16x32_bf16 v[0:3], v[238:241], v[20:23], v[0:3]
	s_waitcnt vmcnt(1)
	v_mfma_f32_16x16x32_bf16 v[88:91], v[4:7], v[16:19], v[8:11]
	v_mfma_f32_16x16x32_bf16 v[92:95], v[92:95], v[16:19], v[12:15]
	v_mfma_f32_16x16x32_bf16 v[108:111], v[108:111], v[16:19], v[24:27]
	v_mfma_f32_16x16x32_bf16 v[30:33], v[112:115], v[16:19], v[30:33]
	v_mfma_f32_16x16x32_bf16 v[34:37], v[116:119], v[16:19], v[34:37]
	v_mfma_f32_16x16x32_bf16 v[38:41], v[120:123], v[16:19], v[38:41]
	v_mfma_f32_16x16x32_bf16 v[42:45], v[124:127], v[16:19], v[42:45]
	v_mfma_f32_16x16x32_bf16 v[46:49], v[128:131], v[16:19], v[46:49]
	s_waitcnt lgkmcnt(11)
	v_mfma_f32_16x16x32_bf16 v[50:53], v[132:135], v[16:19], v[50:53]
	s_waitcnt lgkmcnt(10)
	v_mfma_f32_16x16x32_bf16 v[54:57], v[136:139], v[16:19], v[54:57]
	s_waitcnt lgkmcnt(9)
	v_mfma_f32_16x16x32_bf16 v[24:27], v[140:143], v[16:19], v[58:61]
	s_waitcnt lgkmcnt(8)
	v_mfma_f32_16x16x32_bf16 v[20:23], v[144:147], v[16:19], v[62:65]
	s_waitcnt lgkmcnt(3)
	v_mfma_f32_16x16x32_bf16 v[12:15], v[148:151], v[16:19], v[66:69]
	s_waitcnt lgkmcnt(2)
	v_mfma_f32_16x16x32_bf16 v[8:11], v[156:159], v[16:19], v[70:73]
	s_waitcnt lgkmcnt(1)
	v_mfma_f32_16x16x32_bf16 v[4:7], v[160:163], v[16:19], v[74:77]
	s_waitcnt lgkmcnt(0)
	v_mfma_f32_16x16x32_bf16 v[0:3], v[164:167], v[16:19], v[0:3]
	ds_read2_b64 v[58:61], v81 offset1:4
	v_add_u32_e32 v18, s10, v80
	v_mov_b64_e32 v[16:17], s[38:39]
	v_mad_i64_i32 v[16:17], s[10:11], v18, s34, v[16:17]
	s_waitcnt lgkmcnt(0)
	v_lshlrev_b32_e32 v18, 16, v58
	v_and_b32_e32 v19, 0xffff0000, v58
	s_waitcnt vmcnt(0)
	v_pk_add_f32 v[62:63], v[28:29], v[88:89] op_sel_hi:[0,1]
	v_pk_mul_f32 v[18:19], v[62:63], v[18:19]
	v_lshlrev_b32_e32 v58, 16, v59
	v_and_b32_e32 v59, 0xffff0000, v59
	v_pk_add_f32 v[62:63], v[28:29], v[90:91] op_sel_hi:[0,1]
	v_lshl_add_u64 v[16:17], v[16:17], 0, s[8:9]
	v_mov_b32_e32 v87, v155
	v_pk_mul_f32 v[58:59], v[62:63], v[58:59]
	v_lshl_add_u64 v[16:17], v[16:17], 0, v[86:87]
	v_cvt_pk_bf16_f32 v18, v18, v19
	v_cvt_pk_bf16_f32 v19, v58, v59
	ds_write_b64 v81, v[18:19]
	v_lshlrev_b32_e32 v18, 16, v60
	v_and_b32_e32 v19, 0xffff0000, v60
	v_pk_add_f32 v[58:59], v[28:29], v[92:93] op_sel_hi:[0,1]
	v_pk_mul_f32 v[18:19], v[58:59], v[18:19]
	v_lshlrev_b32_e32 v62, 16, v61
	v_and_b32_e32 v63, 0xffff0000, v61
	ds_read2_b64 v[58:61], v81 offset0:8 offset1:12
	v_pk_add_f32 v[64:65], v[28:29], v[94:95] op_sel_hi:[0,1]
	v_pk_mul_f32 v[62:63], v[64:65], v[62:63]
	v_cvt_pk_bf16_f32 v18, v18, v19
	v_cvt_pk_bf16_f32 v19, v62, v63
	ds_write_b64 v81, v[18:19] offset:32
	s_waitcnt lgkmcnt(0)
	v_lshlrev_b32_e32 v18, 16, v58
	v_and_b32_e32 v19, 0xffff0000, v58
	v_pk_add_f32 v[62:63], v[28:29], v[108:109] op_sel_hi:[0,1]
	v_pk_mul_f32 v[18:19], v[62:63], v[18:19]
	v_lshlrev_b32_e32 v58, 16, v59
	v_and_b32_e32 v59, 0xffff0000, v59
	v_pk_add_f32 v[62:63], v[28:29], v[110:111] op_sel_hi:[0,1]
	v_pk_mul_f32 v[58:59], v[62:63], v[58:59]
	v_cvt_pk_bf16_f32 v18, v18, v19
	v_cvt_pk_bf16_f32 v19, v58, v59
	ds_write_b64 v81, v[18:19] offset:64
	v_lshlrev_b32_e32 v18, 16, v60
	v_and_b32_e32 v19, 0xffff0000, v60
	v_pk_add_f32 v[30:31], v[28:29], v[30:31] op_sel_hi:[0,1]
	v_pk_mul_f32 v[18:19], v[30:31], v[18:19]
	v_lshlrev_b32_e32 v30, 16, v61
	v_and_b32_e32 v31, 0xffff0000, v61
	ds_read2_b64 v[58:61], v81 offset0:16 offset1:20
	v_pk_add_f32 v[32:33], v[28:29], v[32:33] op_sel_hi:[0,1]
	v_pk_mul_f32 v[30:31], v[32:33], v[30:31]
	v_cvt_pk_bf16_f32 v18, v18, v19
	v_cvt_pk_bf16_f32 v19, v30, v31
	ds_write_b64 v81, v[18:19] offset:96
	s_waitcnt lgkmcnt(0)
	v_lshlrev_b32_e32 v18, 16, v58
	v_and_b32_e32 v19, 0xffff0000, v58
	v_pk_add_f32 v[30:31], v[28:29], v[34:35] op_sel_hi:[0,1]
	v_pk_mul_f32 v[18:19], v[30:31], v[18:19]
	v_lshlrev_b32_e32 v30, 16, v59
	v_and_b32_e32 v31, 0xffff0000, v59
	v_pk_add_f32 v[32:33], v[28:29], v[36:37] op_sel_hi:[0,1]
	v_pk_mul_f32 v[30:31], v[32:33], v[30:31]
	v_cvt_pk_bf16_f32 v18, v18, v19
	v_cvt_pk_bf16_f32 v19, v30, v31
	ds_write_b64 v81, v[18:19] offset:128
	v_lshlrev_b32_e32 v18, 16, v60
	v_and_b32_e32 v19, 0xffff0000, v60
	v_pk_add_f32 v[30:31], v[28:29], v[38:39] op_sel_hi:[0,1]
	v_pk_mul_f32 v[18:19], v[30:31], v[18:19]
	ds_read2_b64 v[30:33], v81 offset0:24 offset1:28
	v_lshlrev_b32_e32 v34, 16, v61
	v_and_b32_e32 v35, 0xffff0000, v61
	v_pk_add_f32 v[36:37], v[28:29], v[40:41] op_sel_hi:[0,1]
	v_pk_mul_f32 v[34:35], v[36:37], v[34:35]
	v_cvt_pk_bf16_f32 v18, v18, v19
	v_cvt_pk_bf16_f32 v19, v34, v35
	ds_write_b64 v81, v[18:19] offset:160
	s_waitcnt lgkmcnt(0)
	v_lshlrev_b32_e32 v18, 16, v30
	v_and_b32_e32 v19, 0xffff0000, v30
	v_pk_add_f32 v[34:35], v[28:29], v[42:43] op_sel_hi:[0,1]
	v_pk_mul_f32 v[18:19], v[34:35], v[18:19]
	v_lshlrev_b32_e32 v30, 16, v31
	v_and_b32_e32 v31, 0xffff0000, v31
	v_pk_add_f32 v[34:35], v[28:29], v[44:45] op_sel_hi:[0,1]
	v_pk_mul_f32 v[30:31], v[34:35], v[30:31]
	v_cvt_pk_bf16_f32 v18, v18, v19
	v_cvt_pk_bf16_f32 v19, v30, v31
	ds_write_b64 v81, v[18:19] offset:192
	v_lshlrev_b32_e32 v18, 16, v32
	v_and_b32_e32 v19, 0xffff0000, v32
	v_pk_add_f32 v[30:31], v[28:29], v[46:47] op_sel_hi:[0,1]
	v_pk_mul_f32 v[18:19], v[30:31], v[18:19]
	v_lshlrev_b32_e32 v34, 16, v33
	v_and_b32_e32 v35, 0xffff0000, v33
	ds_read2_b64 v[30:33], v81 offset0:32 offset1:36
	v_pk_add_f32 v[36:37], v[28:29], v[48:49] op_sel_hi:[0,1]
	v_pk_mul_f32 v[34:35], v[36:37], v[34:35]
	v_cvt_pk_bf16_f32 v18, v18, v19
	v_cvt_pk_bf16_f32 v19, v34, v35
	ds_write_b64 v81, v[18:19] offset:224
	s_waitcnt lgkmcnt(0)
	v_lshlrev_b32_e32 v18, 16, v30
	v_and_b32_e32 v19, 0xffff0000, v30
	v_pk_add_f32 v[34:35], v[28:29], v[50:51] op_sel_hi:[0,1]
	v_pk_mul_f32 v[18:19], v[34:35], v[18:19]
	v_lshlrev_b32_e32 v30, 16, v31
	v_and_b32_e32 v31, 0xffff0000, v31
	v_pk_add_f32 v[34:35], v[28:29], v[52:53] op_sel_hi:[0,1]
	v_pk_mul_f32 v[30:31], v[34:35], v[30:31]
	v_cvt_pk_bf16_f32 v18, v18, v19
	v_cvt_pk_bf16_f32 v19, v30, v31
	ds_read2_b64 v[34:37], v81 offset0:40 offset1:44
	ds_write_b64 v81, v[18:19] offset:256
	v_lshlrev_b32_e32 v18, 16, v32
	v_and_b32_e32 v19, 0xffff0000, v32
	v_pk_add_f32 v[30:31], v[28:29], v[54:55] op_sel_hi:[0,1]
	v_pk_mul_f32 v[18:19], v[30:31], v[18:19]
	v_lshlrev_b32_e32 v30, 16, v33
	v_and_b32_e32 v31, 0xffff0000, v33
	v_pk_add_f32 v[32:33], v[28:29], v[56:57] op_sel_hi:[0,1]
	v_pk_mul_f32 v[30:31], v[32:33], v[30:31]
	v_cvt_pk_bf16_f32 v18, v18, v19
	v_cvt_pk_bf16_f32 v19, v30, v31
	ds_write_b64 v81, v[18:19] offset:288
	s_waitcnt lgkmcnt(0)
	v_lshlrev_b32_e32 v18, 16, v34
	v_and_b32_e32 v19, 0xffff0000, v34
	v_pk_add_f32 v[24:25], v[28:29], v[24:25] op_sel_hi:[0,1]
	v_pk_mul_f32 v[18:19], v[24:25], v[18:19]
	v_lshlrev_b32_e32 v24, 16, v35
	v_and_b32_e32 v25, 0xffff0000, v35
	v_pk_add_f32 v[26:27], v[28:29], v[26:27] op_sel_hi:[0,1]
	v_pk_mul_f32 v[24:25], v[26:27], v[24:25]
	v_cvt_pk_bf16_f32 v18, v18, v19
	v_cvt_pk_bf16_f32 v19, v24, v25
	ds_write_b64 v81, v[18:19] offset:320
	v_lshlrev_b32_e32 v18, 16, v36
	v_and_b32_e32 v19, 0xffff0000, v36
	v_pk_add_f32 v[20:21], v[28:29], v[20:21] op_sel_hi:[0,1]
	v_pk_mul_f32 v[18:19], v[20:21], v[18:19]
	v_lshlrev_b32_e32 v26, 16, v37
	v_cvt_pk_bf16_f32 v24, v18, v19
	ds_read2_b64 v[18:21], v81 offset0:48 offset1:52
	v_and_b32_e32 v27, 0xffff0000, v37
	v_pk_add_f32 v[22:23], v[28:29], v[22:23] op_sel_hi:[0,1]
	v_pk_mul_f32 v[22:23], v[22:23], v[26:27]
	v_pk_add_f32 v[12:13], v[28:29], v[12:13] op_sel_hi:[0,1]
	v_cvt_pk_bf16_f32 v25, v22, v23
	s_waitcnt lgkmcnt(0)
	v_lshlrev_b32_e32 v22, 16, v18
	v_and_b32_e32 v23, 0xffff0000, v18
	v_lshlrev_b32_e32 v18, 16, v19
	v_and_b32_e32 v19, 0xffff0000, v19
	v_pk_add_f32 v[14:15], v[28:29], v[14:15] op_sel_hi:[0,1]
	v_pk_mul_f32 v[12:13], v[12:13], v[22:23]
	v_pk_mul_f32 v[14:15], v[14:15], v[18:19]
	v_cvt_pk_bf16_f32 v12, v12, v13
	v_cvt_pk_bf16_f32 v13, v14, v15
	ds_write_b64 v81, v[12:13] offset:384
	v_lshlrev_b32_e32 v12, 16, v20
	v_and_b32_e32 v13, 0xffff0000, v20
	v_pk_add_f32 v[8:9], v[28:29], v[8:9] op_sel_hi:[0,1]
	v_pk_mul_f32 v[8:9], v[8:9], v[12:13]
	ds_read2_b64 v[12:15], v81 offset0:56 offset1:60
	v_lshlrev_b32_e32 v18, 16, v21
	v_and_b32_e32 v19, 0xffff0000, v21
	v_pk_add_f32 v[10:11], v[28:29], v[10:11] op_sel_hi:[0,1]
	v_pk_mul_f32 v[10:11], v[10:11], v[18:19]
	v_cvt_pk_bf16_f32 v8, v8, v9
	v_cvt_pk_bf16_f32 v9, v10, v11
	ds_write_b64 v81, v[8:9] offset:416
	s_waitcnt lgkmcnt(0)
	v_lshlrev_b32_e32 v8, 16, v12
	v_and_b32_e32 v9, 0xffff0000, v12
	v_pk_add_f32 v[4:5], v[28:29], v[4:5] op_sel_hi:[0,1]
	v_pk_mul_f32 v[4:5], v[4:5], v[8:9]
	v_lshlrev_b32_e32 v8, 16, v13
	v_and_b32_e32 v9, 0xffff0000, v13
	v_pk_add_f32 v[6:7], v[28:29], v[6:7] op_sel_hi:[0,1]
	v_pk_mul_f32 v[6:7], v[6:7], v[8:9]
	v_cvt_pk_bf16_f32 v4, v4, v5
	v_cvt_pk_bf16_f32 v5, v6, v7
	ds_write_b64 v81, v[4:5] offset:448
	v_lshlrev_b32_e32 v4, 16, v14
	v_and_b32_e32 v5, 0xffff0000, v14
	v_pk_add_f32 v[0:1], v[28:29], v[0:1] op_sel_hi:[0,1]
	v_pk_mul_f32 v[0:1], v[0:1], v[4:5]
	v_lshlrev_b32_e32 v4, 16, v15
	v_and_b32_e32 v5, 0xffff0000, v15
	v_pk_add_f32 v[2:3], v[28:29], v[2:3] op_sel_hi:[0,1]
	v_pk_mul_f32 v[2:3], v[2:3], v[4:5]
	s_add_i32 s3, s3, s94
	s_add_i32 s2, s2, s30
	v_cvt_pk_bf16_f32 v0, v0, v1
	v_cvt_pk_bf16_f32 v1, v2, v3
	s_cmpk_gt_i32 s3, 0x1ff
	ds_write_b64 v81, v[24:25] offset:352
	ds_write_b64 v81, v[0:1] offset:480
	v_readfirstlane_b32 s98, v16
	v_readfirstlane_b32 s99, v17
	v_readfirstlane_b32 s100, v81
	s_nop 0
	v_add_u32_e32 v250, s100, v249
	s_waitcnt lgkmcnt(0)
	ds_read_b128 v[0:3], v250
	ds_read_b128 v[4:7], v250 offset:1088
	ds_read_b128 v[8:11], v250 offset:2176
	ds_read_b128 v[12:15], v250 offset:3264
	ds_read_b128 v[16:19], v250 offset:4352
	ds_read_b128 v[20:23], v250 offset:5440
	ds_read_b128 v[24:27], v250 offset:6528
	ds_read_b128 v[28:31], v250 offset:7616
	s_waitcnt lgkmcnt(7)
	global_store_dwordx4 v248, v[0:3], s[98:99]
	s_waitcnt lgkmcnt(6)
	s_add_u32 s98, s98, 0x2100
	s_addc_u32 s99, s99, 0
	global_store_dwordx4 v248, v[4:7], s[98:99]
	s_waitcnt lgkmcnt(5)
	s_add_u32 s98, s98, 0x2100
	s_addc_u32 s99, s99, 0
	global_store_dwordx4 v248, v[8:11], s[98:99]
	s_waitcnt lgkmcnt(4)
	s_add_u32 s98, s98, 0x2100
	s_addc_u32 s99, s99, 0
	global_store_dwordx4 v248, v[12:15], s[98:99]
	s_waitcnt lgkmcnt(3)
	s_add_u32 s98, s98, 0x2100
	s_addc_u32 s99, s99, 0
	global_store_dwordx4 v248, v[16:19], s[98:99]
	s_waitcnt lgkmcnt(2)
	s_add_u32 s98, s98, 0x2100
	s_addc_u32 s99, s99, 0
	global_store_dwordx4 v248, v[20:23], s[98:99]
	s_waitcnt lgkmcnt(1)
	s_add_u32 s98, s98, 0x2100
	s_addc_u32 s99, s99, 0
	global_store_dwordx4 v248, v[24:27], s[98:99]
	s_waitcnt lgkmcnt(0)
	s_add_u32 s98, s98, 0x2100
	s_addc_u32 s99, s99, 0
	global_store_dwordx4 v248, v[28:31], s[98:99]
	s_cmpk_gt_i32 s3, 0x1ff
	s_barrier
	s_cbranch_scc0 .LBB0_125
